# seams PB->PC and PF->PA: group flag raised before polling the device-wide conversion counters (publish early, wait late)
# baseline (speedup 1.0000x reference)
; __device__ __forceinline__ unsigned xb_ld(unsigned* p)              { return __hip_atomic_load(p, __ATOMIC_RELAXED, __HIP_MEMORY_SCOPE_AGENT); }
; __device__ __forceinline__ unsigned xb_add(unsigned* p, unsigned v) { return __hip_atomic_fetch_add(p, v, __ATOMIC_RELAXED, __HIP_MEMORY_SCOPE_AGENT); }
; #define XB_SPIN(cond, bar) do { unsigned _sp = 0; while (cond) { __builtin_amdgcn_s_sleep(1); \
;     if ((++_sp & 255u) == 0u) { if (xb_ld(&(bar)[XB_TMO])) break; if (_sp > XB_SPIN_CAP) { atomicAdd(&(bar)[XB_TMO], 1u); break; } } } } while (0)
; #define SEAM_G(k) do { if (IN(k) && IN((k) + 1)) { if (xl_fast) xcc_local_barrier(ctl + CW_BAR2, bar.x, bar.st[0], bar.bar); else xcd_barrier(bar); } } while (0)
; #define SEAM_G(k) SEAM(k)
; __device__ __forceinline__ void xcc_local_barrier(unsigned* bar2, unsigned x, unsigned nloc, unsigned* tmobar) {
;     asm volatile("s_waitcnt vmcnt(0)" ::: "memory");
;     __syncthreads();
;     if (threadIdx.x == 0) {
;         const unsigned old = xb_add(&bar2[XB_XSUB(x)], 1u);
;         const unsigned gen = old / nloc;
;         if (old + 1u == (gen + 1u) * nloc) (void)xb_add(&bar2[XB_XGEN(x)], 1u);
;         else XB_SPIN(xb_ld(&bar2[XB_XGEN(x)]) == gen, tmobar);
;         __builtin_amdgcn_fence(__ATOMIC_ACQUIRE, "agent");
;         asm volatile("s_waitcnt vmcnt(0)" ::: "memory");
;     }
;     __syncthreads();
; }
; __global__ void __launch_bounds__(NWAVES * 64, 2) mk_fwd(Args args) {
;     ...
;         SEAM_G(pb + 1);
;         if (xl_fast && (int)blockIdx.x < 64 && tid == 0) (void)xb_add(ctl + CW_PBD + 64 * (((int)blockIdx.x % 8) * 8 + ((int)blockIdx.x / 8) % 8), 1u);
.LBB0_478:
	s_and_b64 vcc, exec, s[38:39]
	s_cbranch_vccz .LBB0_498
	v_readlane_b32 s6, v238, 25
	s_nop 1
	v_mov_b32_e32 v2, s6
	ds_read_b32 v2, v2
	s_waitcnt vmcnt(0)
	v_readlane_b32 s6, v242, 38
	v_readlane_b32 s7, v242, 39
	s_waitcnt vmcnt(0) lgkmcnt(0)
	s_barrier
	s_and_saveexec_b64 s[38:39], s[6:7]
	s_cbranch_execz .LBB0_497
	s_cmp_ge_u32 s101, 5
	s_cselect_b32 s100, 2, 1
	s_lshl_b32 s100, s100, 8
	s_add_i32 s101, s101, 1
	v_readlane_b32 s6, v239, 63
	v_readlane_b32 s7, v241, 0
	v_readlane_b32 s98, v242, 4
	v_mov_b32_e32 v3, s101
	s_nop 3
	s_lshr_b32 s98, s98, 6
	s_lshl_b32 s98, s98, 2
	v_mov_b32_e32 v4, s98
	global_store_dword v4, v3, s[6:7] offset:128 sc1
	buffer_inv sc1
	v_readlane_b32 s6, v240, 60
	v_readlane_b32 s7, v240, 61
	s_mov_b32 s99, 0
	s_nop 4

; __device__ __forceinline__ unsigned xb_ld(unsigned* p)              { return __hip_atomic_load(p, __ATOMIC_RELAXED, __HIP_MEMORY_SCOPE_AGENT); }
; __device__ __forceinline__ unsigned xb_add(unsigned* p, unsigned v) { return __hip_atomic_fetch_add(p, v, __ATOMIC_RELAXED, __HIP_MEMORY_SCOPE_AGENT); }
; #define XB_SPIN(cond, bar) do { unsigned _sp = 0; while (cond) { __builtin_amdgcn_s_sleep(1); \
;     if ((++_sp & 255u) == 0u) { if (xb_ld(&(bar)[XB_TMO])) break; if (_sp > XB_SPIN_CAP) { atomicAdd(&(bar)[XB_TMO], 1u); break; } } } } while (0)
; __device__ __forceinline__ void xcc_local_barrier(unsigned* bar2, unsigned x, unsigned nloc, unsigned* tmobar) {
;     asm volatile("s_waitcnt vmcnt(0)" ::: "memory");
;     __syncthreads();
;     if (threadIdx.x == 0) {
;         const unsigned old = xb_add(&bar2[XB_XSUB(x)], 1u);
;         const unsigned gen = old / nloc;
;         if (old + 1u == (gen + 1u) * nloc) (void)xb_add(&bar2[XB_XGEN(x)], 1u);
;         else XB_SPIN(xb_ld(&bar2[XB_XGEN(x)]) == gen, tmobar);
;         __builtin_amdgcn_fence(__ATOMIC_ACQUIRE, "agent");
;         asm volatile("s_waitcnt vmcnt(0)" ::: "memory");
;     }
;     __syncthreads();
; }
.Lcv_done:
	v_readlane_b32 s6, v239, 63
	v_readlane_b32 s7, v241, 0
	s_mov_b32 s100, 0
	s_nop 4

; __device__ __forceinline__ unsigned xb_ld(unsigned* p)              { return __hip_atomic_load(p, __ATOMIC_RELAXED, __HIP_MEMORY_SCOPE_AGENT); }
; __device__ __forceinline__ unsigned xb_add(unsigned* p, unsigned v) { return __hip_atomic_fetch_add(p, v, __ATOMIC_RELAXED, __HIP_MEMORY_SCOPE_AGENT); }
; #define XB_SPIN(cond, bar) do { unsigned _sp = 0; while (cond) { __builtin_amdgcn_s_sleep(1); \
;     if ((++_sp & 255u) == 0u) { if (xb_ld(&(bar)[XB_TMO])) break; if (_sp > XB_SPIN_CAP) { atomicAdd(&(bar)[XB_TMO], 1u); break; } } } } while (0)
; #define SEAM(k) do { if (IN(k) && IN((k) + 1)) { xcd_barrier(bar); xcd_barrier(bar); } } while (0)
; #define SEAM(k) do { if (IN(k) && IN((k) + 1)) xcd_barrier(bar); } while (0)
; #define SEAM_G(k) do { if (IN(k) && IN((k) + 1)) { if (xl_fast) xcc_local_barrier(ctl + CW_BAR2, bar.x, bar.st[0], bar.bar); else xcd_barrier(bar); } } while (0)
; #define SEAM_G(k) SEAM(k)
; __device__ __forceinline__ void xcc_local_barrier(unsigned* bar2, unsigned x, unsigned nloc, unsigned* tmobar) {
;     asm volatile("s_waitcnt vmcnt(0)" ::: "memory");
;     __syncthreads();
;     if (threadIdx.x == 0) {
;         const unsigned old = xb_add(&bar2[XB_XSUB(x)], 1u);
;         const unsigned gen = old / nloc;
;         if (old + 1u == (gen + 1u) * nloc) (void)xb_add(&bar2[XB_XGEN(x)], 1u);
;         else XB_SPIN(xb_ld(&bar2[XB_XGEN(x)]) == gen, tmobar);
;         __builtin_amdgcn_fence(__ATOMIC_ACQUIRE, "agent");
;         asm volatile("s_waitcnt vmcnt(0)" ::: "memory");
;     }
;     __syncthreads();
; }
; __global__ void __launch_bounds__(NWAVES * 64, 2) mk_fwd(Args args) {
;     ...
;         if (l == DEPTH - 1) SEAM_G(pb + 5); else SEAM(pb + 5);
.LBB0_932:
	v_readlane_b32 s6, v238, 44
	s_add_i32 s23, s6, 7
	s_cmp_lt_i32 s23, s5
	v_readlane_b32 s6, v238, 51
	s_cselect_b64 s[24:25], -1, 0
	v_readlane_b32 s7, v238, 52
	s_and_b64 s[36:37], s[42:43], s[24:25]
	s_and_b64 vcc, exec, s[6:7]
	s_cbranch_vccz .LBB0_945
	v_readlane_b32 s28, v240, 2
	s_mov_b64 s[38:39], 0
	s_and_b64 vcc, exec, s[36:37]
	s_mov_b64 s[40:41], 0
	v_readlane_b32 s29, v240, 3
	s_cbranch_vccz .LBB0_946
	s_waitcnt vmcnt(0)
	v_readlane_b32 s6, v242, 38
	v_readlane_b32 s7, v242, 39
	s_waitcnt vmcnt(0) lgkmcnt(0)
	s_barrier
	s_and_saveexec_b64 s[40:41], s[6:7]
	s_cbranch_execz .LBB0_1018
	v_readlane_b32 s6, v242, 52
	v_readlane_b32 s7, v242, 53
	s_nop 3
	s_cmp_eq_u64 s[6:7], 0
	s_cbranch_scc0 .Lpf_seam_grid
	s_add_i32 s101, s101, 1
	v_readlane_b32 s6, v239, 63
	v_readlane_b32 s7, v241, 0
	v_readlane_b32 s98, v242, 4
	v_mov_b32_e32 v3, s101
	s_nop 3
	s_lshr_b32 s98, s98, 6
	s_lshl_b32 s98, s98, 2
	v_mov_b32_e32 v4, s98
	global_store_dword v4, v3, s[6:7] offset:128 sc1
	buffer_inv sc1
	v_readlane_b32 s6, v240, 60
	v_readlane_b32 s7, v240, 61
	s_mov_b32 s99, 0
	s_nop 4
